# a36: a35 + .p2align 6 on the 10 GEMM K-loop heads
# baseline (speedup 1.0000x reference)
.Lmy_pr_0:
	.p2align	6
